# v31: GU epilogue two-pair interleave in all 8 blocks (block 0/1 reuse their row-scale register pair as second temp after the scaling step)
# speedup vs baseline: 1.0014x; 1.0014x over previous
; #define PG8_LAS __attribute__((address_space(3)))
; __device__ __forceinline__ u32x4 pack8(const f32x4 a, const f32x4 b) { u32x4 w; w.x = cvt_pk_bf16(a[0], a[1]); w.y = cvt_pk_bf16(a[2], a[3]); w.z = cvt_pk_bf16(b[0], b[1]); w.w = cvt_pk_bf16(b[2], b[3]); return w; }
;     __device__ __forceinline__ void operator()(const f32x4 (&acc)[2][2][4][2], const Unit& u, int wr, int wc, int fr, int fq) const {
;         PG8_LAS const float* R = stage_rstd((const float*)(ws + WS_PS), lds, u.pm);
; #pragma unroll
;         for (int ai = 0; ai < 2; ++ai)
; #pragma unroll
;             for (int m = 0; m < 4; ++m) {
;                 const int row = u.pm * BM + ai * HALF + wr * 64 + m * 16 + fr;
;                 const float rs = R[ai * HALF + wr * 64 + m * 16 + fr];
;                 bf16_t* ACT = (bf16_t*)(ws + WS_ACT);
;                 f32x4 a[2];
; #pragma unroll
;                 for (int n = 0; n < 2; ++n) {
;                     const f32x4 g = acc[ai][0][m][n] * rs, uu = acc[ai][1][m][n] * rs;
; #pragma unroll
;                     for (int j = 0; j < 4; ++j) a[n][j] = g[j] * __builtin_amdgcn_rcpf(1.0f + __builtin_amdgcn_exp2f(-1.4426950408889634f * g[j])) * uu[j];
;                 }
;                 *(u32x4*)(ACT + (size_t)row * 2816 + u.pn * 128 + wc * 32 + 8 * fq) = pack8(a[0], a[1]);
;             }
.LBB0_38:
	s_lshl_b32 s3, s48, 8
	ds_read_b32 v146, v142
	v_mov_b32_e32 v145, 0xbfb8aa3b
	s_waitcnt lgkmcnt(0)
	v_pk_mul_f32 v[124:125], v[124:125], v[146:147] op_sel_hi:[1,0]
	v_pk_mul_f32 v[126:127], v[126:127], v[146:147] op_sel_hi:[1,0]
	v_pk_mul_f32 v[116:117], v[116:117], v[146:147] op_sel_hi:[1,0]
	v_pk_mul_f32 v[118:119], v[118:119], v[146:147] op_sel_hi:[1,0]
	v_pk_mul_f32 v[120:121], v[120:121], v[146:147] op_sel_hi:[1,0]
	v_pk_mul_f32 v[122:123], v[122:123], v[146:147] op_sel_hi:[1,0]
	v_pk_mul_f32 v[112:113], v[112:113], v[146:147] op_sel_hi:[1,0]
	v_pk_mul_f32 v[114:115], v[114:115], v[146:147] op_sel_hi:[1,0]
	v_pk_mul_f32 v[148:149], v[124:125], v[144:145] op_sel:[0,1] op_sel_hi:[1,1]
	v_pk_mul_f32 v[146:147], v[126:127], v[144:145] op_sel:[0,1] op_sel_hi:[1,1]
	v_exp_f32_e32 v148, v148
	v_exp_f32_e32 v149, v149
	v_exp_f32_e32 v146, v146
	v_exp_f32_e32 v147, v147
	v_add_f32_e32 v148, 1.0, v148
	v_add_f32_e32 v149, 1.0, v149
	v_add_f32_e32 v146, 1.0, v146
	v_add_f32_e32 v147, 1.0, v147
	v_rcp_f32_e32 v148, v148
	v_rcp_f32_e32 v149, v149
	v_rcp_f32_e32 v146, v146
	v_rcp_f32_e32 v147, v147
	v_pk_mul_f32 v[124:125], v[124:125], v[148:149]
	v_pk_mul_f32 v[126:127], v[126:127], v[146:147]
	v_pk_mul_f32 v[120:121], v[120:121], v[124:125]
	v_pk_mul_f32 v[122:123], v[122:123], v[126:127]
	v_pk_mul_f32 v[148:149], v[116:117], v[144:145] op_sel:[0,1] op_sel_hi:[1,1]
	v_pk_mul_f32 v[146:147], v[118:119], v[144:145] op_sel:[0,1] op_sel_hi:[1,1]
	v_exp_f32_e32 v148, v148
	v_exp_f32_e32 v149, v149
	v_exp_f32_e32 v146, v146
	v_exp_f32_e32 v147, v147
	v_add_f32_e32 v148, 1.0, v148
	v_add_f32_e32 v149, 1.0, v149
	v_add_f32_e32 v146, 1.0, v146
	v_add_f32_e32 v147, 1.0, v147
	v_rcp_f32_e32 v148, v148
	v_rcp_f32_e32 v149, v149
	v_rcp_f32_e32 v146, v146
	v_rcp_f32_e32 v147, v147
	v_pk_mul_f32 v[116:117], v[116:117], v[148:149]
	v_pk_mul_f32 v[118:119], v[118:119], v[146:147]
	v_pk_mul_f32 v[112:113], v[112:113], v[116:117]
	v_pk_mul_f32 v[114:115], v[114:115], v[118:119]
	v_cvt_pk_bf16_f32 v116, v112, v113
	v_cvt_pk_bf16_f32 v117, v114, v115
	v_cvt_pk_bf16_f32 v114, v120, v121
	v_cvt_pk_bf16_f32 v115, v122, v123
	s_lshl_b32 s0, s47, 7
	v_add_u32_e32 v144, s3, v140
	s_ashr_i32 s1, s0, 31
	s_movk_i32 s3, 0x1600
	s_lshl_b64 s[0:1], s[0:1], 1
	s_andn2_b64 vcc, exec, s[36:37]
	v_mov_b64_e32 v[112:113], s[16:17]
	s_mov_b32 s101, 0
	v_mad_i64_i32 v[118:119], s[4:5], v144, s3, v[112:113]
	v_lshl_add_u64 v[118:119], v[118:119], 0, s[0:1]
	v_lshl_add_u64 v[118:119], v[118:119], 0, s[34:35]
	v_lshl_add_u64 v[118:119], v[118:119], 0, v[184:185]
	global_store_dwordx4 v[118:119], v[114:117], off
	ds_read_b32 v114, v142 offset:64
	ds_read_b32 v120, v142 offset:128
	ds_read_b32 v122, v142 offset:192
	ds_read_b32 v124, v142 offset:512
	ds_read_b32 v126, v142 offset:576
	ds_read_b32 v112, v142 offset:640
	ds_read_b32 v116, v142 offset:704
	v_mov_b32_e32 v146, 1.0
	s_waitcnt lgkmcnt(6)
	v_pk_mul_f32 v[108:109], v[108:109], v[114:115] op_sel_hi:[1,0]
	v_pk_mul_f32 v[110:111], v[110:111], v[114:115] op_sel_hi:[1,0]
	v_pk_mul_f32 v[100:101], v[100:101], v[114:115] op_sel_hi:[1,0]
	v_pk_mul_f32 v[102:103], v[102:103], v[114:115] op_sel_hi:[1,0]
	v_pk_mul_f32 v[104:105], v[104:105], v[114:115] op_sel_hi:[1,0]
	v_pk_mul_f32 v[106:107], v[106:107], v[114:115] op_sel_hi:[1,0]
	v_pk_mul_f32 v[96:97], v[96:97], v[114:115] op_sel_hi:[1,0]
	v_pk_mul_f32 v[98:99], v[98:99], v[114:115] op_sel_hi:[1,0]
	v_pk_mul_f32 v[148:149], v[108:109], v[144:145] op_sel:[0,1] op_sel_hi:[1,1]
	v_pk_mul_f32 v[114:115], v[110:111], v[144:145] op_sel:[0,1] op_sel_hi:[1,1]
	v_exp_f32_e32 v148, v148
	v_exp_f32_e32 v149, v149
	v_exp_f32_e32 v114, v114
	v_exp_f32_e32 v115, v115
	v_pk_add_f32 v[148:149], v[148:149], v[146:147] op_sel_hi:[1,0]
	v_pk_add_f32 v[114:115], v[114:115], v[146:147] op_sel_hi:[1,0]
	v_rcp_f32_e32 v148, v148
	v_rcp_f32_e32 v149, v149
	v_rcp_f32_e32 v114, v114
	v_rcp_f32_e32 v115, v115
	v_pk_mul_f32 v[108:109], v[108:109], v[148:149]
	v_pk_mul_f32 v[110:111], v[110:111], v[114:115]
	v_pk_mul_f32 v[104:105], v[104:105], v[108:109]
	v_pk_mul_f32 v[106:107], v[106:107], v[110:111]
	v_pk_mul_f32 v[148:149], v[100:101], v[144:145] op_sel:[0,1] op_sel_hi:[1,1]
	v_pk_mul_f32 v[114:115], v[102:103], v[144:145] op_sel:[0,1] op_sel_hi:[1,1]
	v_exp_f32_e32 v148, v148
	v_exp_f32_e32 v149, v149
	v_exp_f32_e32 v114, v114
	v_exp_f32_e32 v115, v115
	v_pk_add_f32 v[148:149], v[148:149], v[146:147] op_sel_hi:[1,0]
	v_pk_add_f32 v[114:115], v[114:115], v[146:147] op_sel_hi:[1,0]
	v_rcp_f32_e32 v148, v148
	v_rcp_f32_e32 v149, v149
	v_rcp_f32_e32 v114, v114
	v_rcp_f32_e32 v115, v115
	v_pk_mul_f32 v[100:101], v[100:101], v[148:149]
	v_pk_mul_f32 v[102:103], v[102:103], v[114:115]
	v_pk_mul_f32 v[96:97], v[96:97], v[100:101]
	v_pk_mul_f32 v[98:99], v[98:99], v[102:103]
	v_cvt_pk_bf16_f32 v99, v98, v99
	v_cvt_pk_bf16_f32 v98, v96, v97
	v_cvt_pk_bf16_f32 v96, v104, v105
	v_cvt_pk_bf16_f32 v97, v106, v107
	s_mov_b32 s100, 0x16000
	v_lshl_add_u64 v[100:101], v[118:119], 0, s[100:101]
	global_store_dwordx4 v[100:101], v[96:99], off
	s_waitcnt lgkmcnt(0)
; __device__ __forceinline__ u32x4 pack8(const f32x4 a, const f32x4 b) { u32x4 w; w.x = cvt_pk_bf16(a[0], a[1]); w.y = cvt_pk_bf16(a[2], a[3]); w.z = cvt_pk_bf16(b[0], b[1]); w.w = cvt_pk_bf16(b[2], b[3]); return w; }
;     __device__ __forceinline__ void operator()(const f32x4 (&acc)[2][2][4][2], const Unit& u, int wr, int wc, int fr, int fq) const {
;     ...
;             for (int m = 0; m < 4; ++m) {
;                 const int row = u.pm * BM + ai * HALF + wr * 64 + m * 16 + fr;
;                 const float rs = R[ai * HALF + wr * 64 + m * 16 + fr];
;                 bf16_t* ACT = (bf16_t*)(ws + WS_ACT);
;                 f32x4 a[2];
; #pragma unroll
;                 for (int n = 0; n < 2; ++n) {
;                     const f32x4 g = acc[ai][0][m][n] * rs, uu = acc[ai][1][m][n] * rs;
; #pragma unroll
;                     for (int j = 0; j < 4; ++j) a[n][j] = g[j] * __builtin_amdgcn_rcpf(1.0f + __builtin_amdgcn_exp2f(-1.4426950408889634f * g[j])) * uu[j];
;                 }
;                 *(u32x4*)(ACT + (size_t)row * 2816 + u.pn * 128 + wc * 32 + 8 * fq) = pack8(a[0], a[1]);
;             }
	v_pk_mul_f32 v[92:93], v[92:93], v[120:121] op_sel_hi:[1,0]
	v_pk_mul_f32 v[94:95], v[94:95], v[120:121] op_sel_hi:[1,0]
	v_pk_mul_f32 v[84:85], v[84:85], v[120:121] op_sel_hi:[1,0]
	v_pk_mul_f32 v[86:87], v[86:87], v[120:121] op_sel_hi:[1,0]
	v_pk_mul_f32 v[88:89], v[88:89], v[120:121] op_sel_hi:[1,0]
	v_pk_mul_f32 v[90:91], v[90:91], v[120:121] op_sel_hi:[1,0]
	v_pk_mul_f32 v[80:81], v[80:81], v[120:121] op_sel_hi:[1,0]
	v_pk_mul_f32 v[82:83], v[82:83], v[120:121] op_sel_hi:[1,0]
	v_pk_mul_f32 v[148:149], v[92:93], v[144:145] op_sel:[0,1] op_sel_hi:[1,1]
	v_pk_mul_f32 v[114:115], v[94:95], v[144:145] op_sel:[0,1] op_sel_hi:[1,1]
	v_exp_f32_e32 v148, v148
	v_exp_f32_e32 v149, v149
	v_exp_f32_e32 v114, v114
	v_exp_f32_e32 v115, v115
	v_pk_add_f32 v[148:149], v[148:149], v[146:147] op_sel_hi:[1,0]
	v_pk_add_f32 v[114:115], v[114:115], v[146:147] op_sel_hi:[1,0]
	v_rcp_f32_e32 v148, v148
	v_rcp_f32_e32 v149, v149
	v_rcp_f32_e32 v114, v114
	v_rcp_f32_e32 v115, v115
	v_pk_mul_f32 v[92:93], v[92:93], v[148:149]
	v_pk_mul_f32 v[94:95], v[94:95], v[114:115]
	v_pk_mul_f32 v[88:89], v[88:89], v[92:93]
	v_pk_mul_f32 v[90:91], v[90:91], v[94:95]
	v_pk_mul_f32 v[148:149], v[84:85], v[144:145] op_sel:[0,1] op_sel_hi:[1,1]
	v_pk_mul_f32 v[114:115], v[86:87], v[144:145] op_sel:[0,1] op_sel_hi:[1,1]
	v_exp_f32_e32 v148, v148
	v_exp_f32_e32 v149, v149
	v_exp_f32_e32 v114, v114
	v_exp_f32_e32 v115, v115
	v_pk_add_f32 v[148:149], v[148:149], v[146:147] op_sel_hi:[1,0]
	v_pk_add_f32 v[114:115], v[114:115], v[146:147] op_sel_hi:[1,0]
	v_rcp_f32_e32 v148, v148
	v_rcp_f32_e32 v149, v149
	v_rcp_f32_e32 v114, v114
	v_rcp_f32_e32 v115, v115
	v_pk_mul_f32 v[84:85], v[84:85], v[148:149]
	v_pk_mul_f32 v[86:87], v[86:87], v[114:115]
	v_pk_mul_f32 v[80:81], v[80:81], v[84:85]
	v_pk_mul_f32 v[82:83], v[82:83], v[86:87]
	v_cvt_pk_bf16_f32 v83, v82, v83
	v_cvt_pk_bf16_f32 v82, v80, v81
	v_cvt_pk_bf16_f32 v80, v88, v89
	v_cvt_pk_bf16_f32 v81, v90, v91
	s_mov_b32 s100, 0x2c000
	v_lshl_add_u64 v[84:85], v[118:119], 0, s[100:101]
	global_store_dwordx4 v[84:85], v[80:83], off
	s_waitcnt lgkmcnt(0)
	v_pk_mul_f32 v[76:77], v[76:77], v[122:123] op_sel_hi:[1,0]
	v_pk_mul_f32 v[78:79], v[78:79], v[122:123] op_sel_hi:[1,0]
	v_pk_mul_f32 v[68:69], v[68:69], v[122:123] op_sel_hi:[1,0]
	v_pk_mul_f32 v[70:71], v[70:71], v[122:123] op_sel_hi:[1,0]
	v_pk_mul_f32 v[72:73], v[72:73], v[122:123] op_sel_hi:[1,0]
	v_pk_mul_f32 v[74:75], v[74:75], v[122:123] op_sel_hi:[1,0]
	v_pk_mul_f32 v[64:65], v[64:65], v[122:123] op_sel_hi:[1,0]
	v_pk_mul_f32 v[66:67], v[66:67], v[122:123] op_sel_hi:[1,0]
	v_pk_mul_f32 v[148:149], v[76:77], v[144:145] op_sel:[0,1] op_sel_hi:[1,1]
	v_pk_mul_f32 v[114:115], v[78:79], v[144:145] op_sel:[0,1] op_sel_hi:[1,1]
	v_exp_f32_e32 v148, v148
	v_exp_f32_e32 v149, v149
	v_exp_f32_e32 v114, v114
	v_exp_f32_e32 v115, v115
	v_pk_add_f32 v[148:149], v[148:149], v[146:147] op_sel_hi:[1,0]
	v_pk_add_f32 v[114:115], v[114:115], v[146:147] op_sel_hi:[1,0]
	v_rcp_f32_e32 v148, v148
	v_rcp_f32_e32 v149, v149
	v_rcp_f32_e32 v114, v114
	v_rcp_f32_e32 v115, v115
	v_pk_mul_f32 v[76:77], v[76:77], v[148:149]
	v_pk_mul_f32 v[78:79], v[78:79], v[114:115]
	v_pk_mul_f32 v[72:73], v[72:73], v[76:77]
	v_pk_mul_f32 v[74:75], v[74:75], v[78:79]
	v_pk_mul_f32 v[148:149], v[68:69], v[144:145] op_sel:[0,1] op_sel_hi:[1,1]
	v_pk_mul_f32 v[114:115], v[70:71], v[144:145] op_sel:[0,1] op_sel_hi:[1,1]
	v_exp_f32_e32 v148, v148
	v_exp_f32_e32 v149, v149
	v_exp_f32_e32 v114, v114
	v_exp_f32_e32 v115, v115
	v_pk_add_f32 v[148:149], v[148:149], v[146:147] op_sel_hi:[1,0]
	v_pk_add_f32 v[114:115], v[114:115], v[146:147] op_sel_hi:[1,0]
	v_rcp_f32_e32 v148, v148
	v_rcp_f32_e32 v149, v149
	v_rcp_f32_e32 v114, v114
	v_rcp_f32_e32 v115, v115
	v_pk_mul_f32 v[68:69], v[68:69], v[148:149]
	v_pk_mul_f32 v[70:71], v[70:71], v[114:115]
	v_pk_mul_f32 v[64:65], v[64:65], v[68:69]
	v_pk_mul_f32 v[66:67], v[66:67], v[70:71]
	v_cvt_pk_bf16_f32 v67, v66, v67
	v_cvt_pk_bf16_f32 v66, v64, v65
	v_cvt_pk_bf16_f32 v64, v72, v73
	v_cvt_pk_bf16_f32 v65, v74, v75
	s_mov_b32 s100, 0x42000
	v_lshl_add_u64 v[68:69], v[118:119], 0, s[100:101]
	global_store_dwordx4 v[68:69], v[64:67], off
	s_waitcnt lgkmcnt(0)
	v_pk_mul_f32 v[60:61], v[60:61], v[124:125] op_sel_hi:[1,0]
	v_pk_mul_f32 v[62:63], v[62:63], v[124:125] op_sel_hi:[1,0]
	v_pk_mul_f32 v[52:53], v[52:53], v[124:125] op_sel_hi:[1,0]
	v_pk_mul_f32 v[54:55], v[54:55], v[124:125] op_sel_hi:[1,0]
	v_pk_mul_f32 v[56:57], v[56:57], v[124:125] op_sel_hi:[1,0]
	v_pk_mul_f32 v[58:59], v[58:59], v[124:125] op_sel_hi:[1,0]
	v_pk_mul_f32 v[48:49], v[48:49], v[124:125] op_sel_hi:[1,0]
	v_pk_mul_f32 v[50:51], v[50:51], v[124:125] op_sel_hi:[1,0]
	v_pk_mul_f32 v[148:149], v[60:61], v[144:145] op_sel:[0,1] op_sel_hi:[1,1]
	v_pk_mul_f32 v[114:115], v[62:63], v[144:145] op_sel:[0,1] op_sel_hi:[1,1]
	v_exp_f32_e32 v148, v148
	v_exp_f32_e32 v149, v149
	v_exp_f32_e32 v114, v114
	v_exp_f32_e32 v115, v115
	v_pk_add_f32 v[148:149], v[148:149], v[146:147] op_sel_hi:[1,0]
	v_pk_add_f32 v[114:115], v[114:115], v[146:147] op_sel_hi:[1,0]
	v_rcp_f32_e32 v148, v148
	v_rcp_f32_e32 v149, v149
	v_rcp_f32_e32 v114, v114
	v_rcp_f32_e32 v115, v115
	v_pk_mul_f32 v[60:61], v[60:61], v[148:149]
	v_pk_mul_f32 v[62:63], v[62:63], v[114:115]
	v_pk_mul_f32 v[56:57], v[56:57], v[60:61]
	v_pk_mul_f32 v[58:59], v[58:59], v[62:63]
	v_pk_mul_f32 v[148:149], v[52:53], v[144:145] op_sel:[0,1] op_sel_hi:[1,1]
	v_pk_mul_f32 v[114:115], v[54:55], v[144:145] op_sel:[0,1] op_sel_hi:[1,1]
	v_exp_f32_e32 v148, v148
	v_exp_f32_e32 v149, v149
	v_exp_f32_e32 v114, v114
	v_exp_f32_e32 v115, v115
	v_pk_add_f32 v[148:149], v[148:149], v[146:147] op_sel_hi:[1,0]
	v_pk_add_f32 v[114:115], v[114:115], v[146:147] op_sel_hi:[1,0]
	v_rcp_f32_e32 v148, v148
	v_rcp_f32_e32 v149, v149
	v_rcp_f32_e32 v114, v114
	v_rcp_f32_e32 v115, v115
	v_pk_mul_f32 v[52:53], v[52:53], v[148:149]
	v_pk_mul_f32 v[54:55], v[54:55], v[114:115]
	v_pk_mul_f32 v[48:49], v[48:49], v[52:53]
	v_pk_mul_f32 v[50:51], v[50:51], v[54:55]
	v_cvt_pk_bf16_f32 v51, v50, v51
	v_cvt_pk_bf16_f32 v50, v48, v49
	v_cvt_pk_bf16_f32 v48, v56, v57
	v_cvt_pk_bf16_f32 v49, v58, v59
	s_mov_b32 s100, 0xb0000
	v_lshl_add_u64 v[52:53], v[118:119], 0, s[100:101]
	global_store_dwordx4 v[52:53], v[48:51], off
	s_waitcnt lgkmcnt(0)
; __device__ __forceinline__ u32x4 pack8(const f32x4 a, const f32x4 b) { u32x4 w; w.x = cvt_pk_bf16(a[0], a[1]); w.y = cvt_pk_bf16(a[2], a[3]); w.z = cvt_pk_bf16(b[0], b[1]); w.w = cvt_pk_bf16(b[2], b[3]); return w; }
;     __device__ __forceinline__ void operator()(const f32x4 (&acc)[2][2][4][2], const Unit& u, int wr, int wc, int fr, int fq) const {
;     ...
;             for (int m = 0; m < 4; ++m) {
;                 const int row = u.pm * BM + ai * HALF + wr * 64 + m * 16 + fr;
;                 const float rs = R[ai * HALF + wr * 64 + m * 16 + fr];
;                 bf16_t* ACT = (bf16_t*)(ws + WS_ACT);
;                 f32x4 a[2];
; #pragma unroll
;                 for (int n = 0; n < 2; ++n) {
;                     const f32x4 g = acc[ai][0][m][n] * rs, uu = acc[ai][1][m][n] * rs;
; #pragma unroll
;                     for (int j = 0; j < 4; ++j) a[n][j] = g[j] * __builtin_amdgcn_rcpf(1.0f + __builtin_amdgcn_exp2f(-1.4426950408889634f * g[j])) * uu[j];
;                 }
;                 *(u32x4*)(ACT + (size_t)row * 2816 + u.pn * 128 + wc * 32 + 8 * fq) = pack8(a[0], a[1]);
;             }
	v_pk_mul_f32 v[44:45], v[44:45], v[126:127] op_sel_hi:[1,0]
	v_pk_mul_f32 v[46:47], v[46:47], v[126:127] op_sel_hi:[1,0]
	v_pk_mul_f32 v[36:37], v[36:37], v[126:127] op_sel_hi:[1,0]
	v_pk_mul_f32 v[38:39], v[38:39], v[126:127] op_sel_hi:[1,0]
	v_pk_mul_f32 v[40:41], v[40:41], v[126:127] op_sel_hi:[1,0]
	v_pk_mul_f32 v[42:43], v[42:43], v[126:127] op_sel_hi:[1,0]
	v_pk_mul_f32 v[32:33], v[32:33], v[126:127] op_sel_hi:[1,0]
	v_pk_mul_f32 v[34:35], v[34:35], v[126:127] op_sel_hi:[1,0]
	v_pk_mul_f32 v[148:149], v[44:45], v[144:145] op_sel:[0,1] op_sel_hi:[1,1]
	v_pk_mul_f32 v[114:115], v[46:47], v[144:145] op_sel:[0,1] op_sel_hi:[1,1]
	v_exp_f32_e32 v148, v148
	v_exp_f32_e32 v149, v149
	v_exp_f32_e32 v114, v114
	v_exp_f32_e32 v115, v115
	v_pk_add_f32 v[148:149], v[148:149], v[146:147] op_sel_hi:[1,0]
	v_pk_add_f32 v[114:115], v[114:115], v[146:147] op_sel_hi:[1,0]
	v_rcp_f32_e32 v148, v148
	v_rcp_f32_e32 v149, v149
	v_rcp_f32_e32 v114, v114
	v_rcp_f32_e32 v115, v115
	v_pk_mul_f32 v[44:45], v[44:45], v[148:149]
	v_pk_mul_f32 v[46:47], v[46:47], v[114:115]
	v_pk_mul_f32 v[40:41], v[40:41], v[44:45]
	v_pk_mul_f32 v[42:43], v[42:43], v[46:47]
	v_pk_mul_f32 v[148:149], v[36:37], v[144:145] op_sel:[0,1] op_sel_hi:[1,1]
	v_pk_mul_f32 v[114:115], v[38:39], v[144:145] op_sel:[0,1] op_sel_hi:[1,1]
	v_exp_f32_e32 v148, v148
	v_exp_f32_e32 v149, v149
	v_exp_f32_e32 v114, v114
	v_exp_f32_e32 v115, v115
	v_pk_add_f32 v[148:149], v[148:149], v[146:147] op_sel_hi:[1,0]
	v_pk_add_f32 v[114:115], v[114:115], v[146:147] op_sel_hi:[1,0]
	v_rcp_f32_e32 v148, v148
	v_rcp_f32_e32 v149, v149
	v_rcp_f32_e32 v114, v114
	v_rcp_f32_e32 v115, v115
	v_pk_mul_f32 v[36:37], v[36:37], v[148:149]
	v_pk_mul_f32 v[38:39], v[38:39], v[114:115]
	v_pk_mul_f32 v[32:33], v[32:33], v[36:37]
	v_pk_mul_f32 v[34:35], v[34:35], v[38:39]
	v_cvt_pk_bf16_f32 v35, v34, v35
	v_cvt_pk_bf16_f32 v34, v32, v33
	v_cvt_pk_bf16_f32 v32, v40, v41
	v_cvt_pk_bf16_f32 v33, v42, v43
	s_mov_b32 s100, 0xc6000
	v_lshl_add_u64 v[36:37], v[118:119], 0, s[100:101]
	global_store_dwordx4 v[36:37], v[32:35], off
	s_waitcnt lgkmcnt(0)
	v_pk_mul_f32 v[28:29], v[28:29], v[112:113] op_sel_hi:[1,0]
	v_pk_mul_f32 v[30:31], v[30:31], v[112:113] op_sel_hi:[1,0]
	v_pk_mul_f32 v[20:21], v[20:21], v[112:113] op_sel_hi:[1,0]
	v_pk_mul_f32 v[22:23], v[22:23], v[112:113] op_sel_hi:[1,0]
	v_pk_mul_f32 v[24:25], v[24:25], v[112:113] op_sel_hi:[1,0]
	v_pk_mul_f32 v[26:27], v[26:27], v[112:113] op_sel_hi:[1,0]
	v_pk_mul_f32 v[16:17], v[16:17], v[112:113] op_sel_hi:[1,0]
	v_pk_mul_f32 v[18:19], v[18:19], v[112:113] op_sel_hi:[1,0]
	v_pk_mul_f32 v[148:149], v[28:29], v[144:145] op_sel:[0,1] op_sel_hi:[1,1]
	v_pk_mul_f32 v[114:115], v[30:31], v[144:145] op_sel:[0,1] op_sel_hi:[1,1]
	v_exp_f32_e32 v148, v148
	v_exp_f32_e32 v149, v149
	v_exp_f32_e32 v114, v114
	v_exp_f32_e32 v115, v115
	v_pk_add_f32 v[148:149], v[148:149], v[146:147] op_sel_hi:[1,0]
	v_pk_add_f32 v[114:115], v[114:115], v[146:147] op_sel_hi:[1,0]
	v_rcp_f32_e32 v148, v148
	v_rcp_f32_e32 v149, v149
	v_rcp_f32_e32 v114, v114
	v_rcp_f32_e32 v115, v115
	v_pk_mul_f32 v[28:29], v[28:29], v[148:149]
	v_pk_mul_f32 v[30:31], v[30:31], v[114:115]
	v_pk_mul_f32 v[24:25], v[24:25], v[28:29]
	v_pk_mul_f32 v[26:27], v[26:27], v[30:31]
	v_pk_mul_f32 v[148:149], v[20:21], v[144:145] op_sel:[0,1] op_sel_hi:[1,1]
	v_pk_mul_f32 v[114:115], v[22:23], v[144:145] op_sel:[0,1] op_sel_hi:[1,1]
	v_exp_f32_e32 v148, v148
	v_exp_f32_e32 v149, v149
	v_exp_f32_e32 v114, v114
	v_exp_f32_e32 v115, v115
	v_pk_add_f32 v[148:149], v[148:149], v[146:147] op_sel_hi:[1,0]
	v_pk_add_f32 v[114:115], v[114:115], v[146:147] op_sel_hi:[1,0]
	v_rcp_f32_e32 v148, v148
	v_rcp_f32_e32 v149, v149
	v_rcp_f32_e32 v114, v114
	v_rcp_f32_e32 v115, v115
	v_pk_mul_f32 v[20:21], v[20:21], v[148:149]
	v_pk_mul_f32 v[22:23], v[22:23], v[114:115]
	v_pk_mul_f32 v[16:17], v[16:17], v[20:21]
	v_pk_mul_f32 v[18:19], v[18:19], v[22:23]
	v_cvt_pk_bf16_f32 v19, v18, v19
	v_cvt_pk_bf16_f32 v18, v16, v17
	v_cvt_pk_bf16_f32 v16, v24, v25
	v_cvt_pk_bf16_f32 v17, v26, v27
	s_mov_b32 s100, 0xdc000
	v_lshl_add_u64 v[20:21], v[118:119], 0, s[100:101]
	global_store_dwordx4 v[20:21], v[16:19], off
	s_waitcnt lgkmcnt(0)
	v_pk_mul_f32 v[12:13], v[12:13], v[116:117] op_sel_hi:[1,0]
	v_pk_mul_f32 v[14:15], v[14:15], v[116:117] op_sel_hi:[1,0]
	v_pk_mul_f32 v[4:5], v[4:5], v[116:117] op_sel_hi:[1,0]
	v_pk_mul_f32 v[6:7], v[6:7], v[116:117] op_sel_hi:[1,0]
	v_pk_mul_f32 v[8:9], v[8:9], v[116:117] op_sel_hi:[1,0]
	v_pk_mul_f32 v[10:11], v[10:11], v[116:117] op_sel_hi:[1,0]
	v_pk_mul_f32 v[0:1], v[0:1], v[116:117] op_sel_hi:[1,0]
	v_pk_mul_f32 v[2:3], v[2:3], v[116:117] op_sel_hi:[1,0]
	v_pk_mul_f32 v[148:149], v[12:13], v[144:145] op_sel:[0,1] op_sel_hi:[1,1]
	v_pk_mul_f32 v[114:115], v[14:15], v[144:145] op_sel:[0,1] op_sel_hi:[1,1]
	v_exp_f32_e32 v148, v148
	v_exp_f32_e32 v149, v149
	v_exp_f32_e32 v114, v114
	v_exp_f32_e32 v115, v115
	v_pk_add_f32 v[148:149], v[148:149], v[146:147] op_sel_hi:[1,0]
	v_pk_add_f32 v[114:115], v[114:115], v[146:147] op_sel_hi:[1,0]
	v_rcp_f32_e32 v148, v148
	v_rcp_f32_e32 v149, v149
	v_rcp_f32_e32 v114, v114
	v_rcp_f32_e32 v115, v115
	v_pk_mul_f32 v[12:13], v[12:13], v[148:149]
	v_pk_mul_f32 v[14:15], v[14:15], v[114:115]
	v_pk_mul_f32 v[8:9], v[8:9], v[12:13]
	v_pk_mul_f32 v[10:11], v[10:11], v[14:15]
	v_pk_mul_f32 v[148:149], v[4:5], v[144:145] op_sel:[0,1] op_sel_hi:[1,1]
	v_pk_mul_f32 v[114:115], v[6:7], v[144:145] op_sel:[0,1] op_sel_hi:[1,1]
	v_exp_f32_e32 v148, v148
	v_exp_f32_e32 v149, v149
	v_exp_f32_e32 v114, v114
	v_exp_f32_e32 v115, v115
	v_pk_add_f32 v[148:149], v[148:149], v[146:147] op_sel_hi:[1,0]
	v_pk_add_f32 v[114:115], v[114:115], v[146:147] op_sel_hi:[1,0]
	v_rcp_f32_e32 v148, v148
	v_rcp_f32_e32 v149, v149
	v_rcp_f32_e32 v114, v114
	v_rcp_f32_e32 v115, v115
	v_pk_mul_f32 v[4:5], v[4:5], v[148:149]
	v_pk_mul_f32 v[6:7], v[6:7], v[114:115]
	v_pk_mul_f32 v[0:1], v[0:1], v[4:5]
	v_pk_mul_f32 v[2:3], v[2:3], v[6:7]
	v_cvt_pk_bf16_f32 v3, v2, v3
	v_cvt_pk_bf16_f32 v2, v0, v1
	v_cvt_pk_bf16_f32 v0, v8, v9
	v_cvt_pk_bf16_f32 v1, v10, v11
	s_mov_b32 s100, 0xf2000
	v_lshl_add_u64 v[4:5], v[118:119], 0, s[100:101]
	s_mov_b64 s[0:1], -1
	global_store_dwordx4 v[4:5], v[0:3], off
	s_cbranch_vccnz .LBB0_31
	s_andn2_b64 vcc, exec, s[8:9]
	s_cbranch_vccnz .LBB0_30
	s_barrier
	s_branch .LBB0_30
